# GEMM phase prologues: all 14 staging DMAs issued back to back, single vmcnt(6) wait and one all-wave barrier, lagging half offset barrier moved after it (7 instances)
# speedup vs baseline: 1.0013x; 1.0013x over previous
; #define PG8_STAGE(bufoff, gbase, voff) do { _Pragma("unroll") for (int _i = 0; _i < 2; ++_i) \
;         __builtin_amdgcn_global_load_lds((const unsigned*)((const char*)(gbase) + (voff)[_i]), (LAS unsigned*)(lds + (bufoff) + ldsw + _i * 8192), 16, 0, 0); } while (0)
; #define PG8_WAIT_V(n) asm volatile("s_waitcnt vmcnt(" #n ")" ::: "memory")
; #define PG8_BAR __builtin_amdgcn_s_barrier()
; template <class Epi, class Order = StaticOrder, bool HALFN = false>
; __device__ __forceinline__ void gemm_phase(LAS unsigned char* lds, const Gemm g, const Epi& E) {
;     ...
;     for (int i = 0; i < 2; ++i) { int R, C; stage_rc(tid * 16 + i * 8192, R, C); const int Rb = (R & ~31) + perm32(R & 31);
;         voffA[i] = (unsigned)(R * g.lda + C) * 2u; voffB[i] = (unsigned)(Rb * g.ldb + C) * 2u; }
;     const size_t kstep = (size_t)(BK * 2);
;     const size_t hstepA = (size_t)HALF * g.lda * 2, hstepB = (size_t)HALF * g.ldb * 2;
;     const size_t tstepA = 2 * hstepA, tstepB = 2 * hstepB;
;     const unsigned ldsw = (unsigned)wid * 1024u;
;     const int aoff = lds_byte(wr * 64 + fr, fq * 8), boff = lds_byte(wc * 32 + fr, fq * 8);
;     ...
;     PG8_STAGE(PG8_SB(0, 0), cB, voffB); PG8_STAGE(PG8_SB(0, 1), cB + hstepB, voffB); PG8_STAGE(PG8_SA(0, 0), cA, voffA); PG8_STAGE(PG8_SA(0, 1), cA + hstepA, voffA);
;     if (wr == 1) PG8_BAR;
;     PG8_WAIT_V(2); PG8_BAR;
;     PG8_STAGE(PG8_SB(1, 0), cB + kstep, voffB); PG8_STAGE(PG8_SA(1, 0), cA + kstep, voffA); PG8_STAGE(PG8_SB(1, 1), cB + hstepB + kstep, voffB);
;     PG8_WAIT_V(6); PG8_BAR;
.LBB0_183:
	s_lshl_b32 s83, s6, 6
	s_lshl_b32 s9, s6, 13
	s_lshl_b32 s6, s7, 5
	s_and_b32 s89, s6, 0x60
	s_add_i32 m0, s53, 0x18000
	v_lshl_add_u64 v[8:9], v[8:9], 0, s[60:61]
	s_lshl_b32 s16, s89, 7
	s_nop 0
	global_load_lds_dwordx4 v[8:9], off
	v_lshl_add_u64 v[6:7], v[6:7], 0, s[60:61]
	s_add_i32 m0, s53, 0x1a000
	s_add_i32 s95, s53, 0x8000
	s_add_i32 s15, s53, 0xa000
	global_load_lds_dwordx4 v[6:7], off
	v_lshl_add_u64 v[2:3], v[2:3], 0, s[60:61]
	s_mov_b32 m0, s95
	s_add_u32 s6, s4, 0x80080
	global_load_lds_dwordx4 v[2:3], off
	v_lshl_add_u64 v[2:3], v[4:5], 0, s[60:61]
	s_mov_b32 m0, s15
	s_addc_u32 s7, s5, 0
	global_load_lds_dwordx4 v[2:3], off
	s_add_i32 m0, s53, 0x1c000
	v_lshl_add_u64 v[2:3], s[6:7], 0, v[132:133]
	global_load_lds_dwordx4 v[2:3], off
	v_lshl_add_u64 v[2:3], s[6:7], 0, v[136:137]
	s_add_i32 m0, s53, 0x1e000
	v_bfe_u32 v143, v10, 4, 2
	global_load_lds_dwordx4 v[2:3], off
	v_and_b32_e32 v1, 15, v10
	v_lshlrev_b32_e32 v2, 4, v143
	v_lshlrev_b32_e32 v3, 2, v10
	v_lshl_or_b32 v2, v1, 6, v2
	v_and_b32_e32 v3, 32, v3
	v_bitop3_b32 v4, v2, s9, v3 bitop3:0xde
	v_bitop3_b32 v145, v2, s16, v3 bitop3:0xde
	v_lshlrev_b32_e32 v2, 15, v11
	v_and_b32_e32 v2, 0xffff0000, v2
	v_lshl_add_u32 v2, v12, 12, v2
	v_and_b32_e32 v3, 1, v11
	v_lshl_or_b32 v2, v3, 6, v2
	v_lshl_add_u32 v138, v13, 1, v2
	v_lshlrev_b32_e32 v2, 15, v14
	v_and_b32_e32 v2, 0xffff0000, v2
	s_waitcnt vmcnt(6)
	v_lshl_add_u32 v2, v15, 12, v2
	v_and_b32_e32 v3, 1, v14
	s_cmpk_lt_u32 s8, 0x100
	v_lshl_or_b32 v2, v3, 6, v2
	s_cselect_b64 s[46:47], -1, 0
	s_or_b32 s27, s89, 0xffffdc00
	s_or_b32 s28, s89, 0xfffff400
	s_or_b32 s29, s89, 0x400
	s_or_b32 s16, s89, 0xfffff800
	v_mov_b32_e32 v139, v0
	v_lshl_add_u32 v140, v16, 1, v2
	v_mov_b32_e32 v141, v0
	s_mov_b32 s17, 0
	v_add_u32_e32 v147, 0, v4
	s_barrier
	v_readfirstlane_b32 s98, v188
	s_cmp_lt_u32 s98, 0x100
	s_cbranch_scc1 .Lfill_skip0
	s_barrier

; #define PG8_STAGE(bufoff, gbase, voff) do { _Pragma("unroll") for (int _i = 0; _i < 2; ++_i) \
;         __builtin_amdgcn_global_load_lds((const unsigned*)((const char*)(gbase) + (voff)[_i]), (LAS unsigned*)(lds + (bufoff) + ldsw + _i * 8192), 16, 0, 0); } while (0)
; #define PG8_WAIT_V(n) asm volatile("s_waitcnt vmcnt(" #n ")" ::: "memory")
; #define PG8_BAR __builtin_amdgcn_s_barrier()
; template <class Epi, class Order = StaticOrder, bool HALFN = false>
; __device__ __forceinline__ void gemm_phase(LAS unsigned char* lds, const Gemm g, const Epi& E) {
;     ...
;     for (int i = 0; i < 2; ++i) { int R, C; stage_rc(tid * 16 + i * 8192, R, C); const int Rb = (R & ~31) + perm32(R & 31);
;         voffA[i] = (unsigned)(R * g.lda + C) * 2u; voffB[i] = (unsigned)(Rb * g.ldb + C) * 2u; }
;     const size_t kstep = (size_t)(BK * 2);
;     const size_t hstepA = (size_t)HALF * g.lda * 2, hstepB = (size_t)HALF * g.ldb * 2;
;     const size_t tstepA = 2 * hstepA, tstepB = 2 * hstepB;
;     const unsigned ldsw = (unsigned)wid * 1024u;
;     const int aoff = lds_byte(wr * 64 + fr, fq * 8), boff = lds_byte(wc * 32 + fr, fq * 8);
;     ...
;     PG8_STAGE(PG8_SB(0, 0), cB, voffB); PG8_STAGE(PG8_SB(0, 1), cB + hstepB, voffB); PG8_STAGE(PG8_SA(0, 0), cA, voffA); PG8_STAGE(PG8_SA(0, 1), cA + hstepA, voffA);
;     if (wr == 1) PG8_BAR;
;     PG8_WAIT_V(2); PG8_BAR;
;     PG8_STAGE(PG8_SB(1, 0), cB + kstep, voffB); PG8_STAGE(PG8_SA(1, 0), cA + kstep, voffA); PG8_STAGE(PG8_SB(1, 1), cB + hstepB + kstep, voffB);
;     PG8_WAIT_V(6); PG8_BAR;
.LBB0_232:
	v_bfe_u32 v79, v14, 4, 2
	v_and_b32_e32 v1, 15, v14
	v_lshlrev_b32_e32 v17, 4, v79
	v_lshlrev_b32_e32 v14, 2, v14
	s_lshl_b32 s22, s7, 6
	v_lshl_or_b32 v17, v1, 6, v17
	s_lshl_b32 s7, s7, 13
	v_and_b32_e32 v14, 32, v14
	v_bitop3_b32 v18, v17, s7, v14 bitop3:0xde
	s_lshl_b32 s7, s8, 5
	s_and_b32 s23, s7, 0x60
	s_add_i32 m0, s16, 0x18000
	v_lshl_add_u64 v[8:9], v[8:9], 0, s[60:61]
	s_lshl_b32 s7, s23, 7
	s_nop 0
	global_load_lds_dwordx4 v[8:9], off
	v_lshl_add_u64 v[6:7], v[6:7], 0, s[60:61]
	s_add_i32 m0, s16, 0x1a000
	s_add_i32 s51, s16, 0x8000
	s_add_i32 s53, s16, 0xa000
	global_load_lds_dwordx4 v[6:7], off
	v_lshl_add_u64 v[2:3], v[2:3], 0, s[60:61]
	s_mov_b32 m0, s51
	s_add_u32 s8, s4, 0x80080
	global_load_lds_dwordx4 v[2:3], off
	v_lshl_add_u64 v[2:3], v[4:5], 0, s[60:61]
	s_mov_b32 m0, s53
	s_addc_u32 s9, s5, 0
	s_add_i32 s56, s16, 0x1c000
	global_load_lds_dwordx4 v[2:3], off
	v_lshl_add_u64 v[2:3], s[8:9], 0, v[68:69]
	s_mov_b32 m0, s56
	s_add_i32 s81, s16, 0x1e000
	global_load_lds_dwordx4 v[2:3], off
	v_lshl_add_u64 v[2:3], s[8:9], 0, v[72:73]
	s_mov_b32 m0, s81
	s_cmpk_lt_u32 s6, 0x100
	global_load_lds_dwordx4 v[2:3], off
	v_lshlrev_b32_e32 v2, 15, v10
	v_and_b32_e32 v2, 0xffff0000, v2
	v_lshl_add_u32 v2, v11, 12, v2
	v_and_b32_e32 v3, 1, v10
	v_lshl_or_b32 v2, v3, 6, v2
	v_lshl_add_u32 v74, v12, 1, v2
	v_lshlrev_b32_e32 v2, 15, v13
	v_and_b32_e32 v2, 0xffff0000, v2
	s_waitcnt vmcnt(6)
	v_lshl_add_u32 v2, v15, 12, v2
	v_and_b32_e32 v3, 1, v13
	v_lshl_or_b32 v2, v3, 6, v2
	v_bitop3_b32 v81, v17, s7, v14 bitop3:0xde
	s_cselect_b64 s[48:49], -1, 0
	s_or_b32 s36, s23, 0xfffff400
	s_or_b32 s37, s23, 0x400
	s_or_b32 s89, s23, 0xfffff800
	s_or_b32 s79, s23, 0xffffdc00
	v_mov_b32_e32 v75, v0
	v_lshl_add_u32 v76, v16, 1, v2
	v_mov_b32_e32 v77, v0
	s_mov_b32 s24, 0
	v_add_u32_e32 v83, 0, v18
	s_barrier
	v_readfirstlane_b32 s98, v188
	s_cmp_lt_u32 s98, 0x100
	s_cbranch_scc1 .Lfill_skip1
	s_barrier

; #define PG8_STAGE(bufoff, gbase, voff) do { _Pragma("unroll") for (int _i = 0; _i < 2; ++_i) \
;         __builtin_amdgcn_global_load_lds((const unsigned*)((const char*)(gbase) + (voff)[_i]), (LAS unsigned*)(lds + (bufoff) + ldsw + _i * 8192), 16, 0, 0); } while (0)
; #define PG8_WAIT_V(n) asm volatile("s_waitcnt vmcnt(" #n ")" ::: "memory")
; #define PG8_BAR __builtin_amdgcn_s_barrier()
; template <class Epi, class Order = StaticOrder, bool HALFN = false>
; __device__ __forceinline__ void gemm_phase(LAS unsigned char* lds, const Gemm g, const Epi& E) {
;     ...
;     Order S; S.init(g.nM, g.nN, (int)gridDim.x, (int)blockIdx.x); S.lx = g.lx; S.lr = g.lr;
;     unsigned voffA[2], voffB[2];
; #pragma unroll
;     for (int i = 0; i < 2; ++i) { int R, C; stage_rc(tid * 16 + i * 8192, R, C); const int Rb = (R & ~31) + perm32(R & 31);
;         voffA[i] = (unsigned)(R * g.lda + C) * 2u; voffB[i] = (unsigned)(Rb * g.ldb + C) * 2u; }
;     const size_t kstep = (size_t)(BK * 2);
;     const size_t hstepA = (size_t)HALF * g.lda * 2, hstepB = (size_t)HALF * g.ldb * 2;
;     const size_t tstepA = 2 * hstepA, tstepB = 2 * hstepB;
;     const unsigned ldsw = (unsigned)wid * 1024u;
;     const int aoff = lds_byte(wr * 64 + fr, fq * 8), boff = lds_byte(wc * 32 + fr, fq * 8);
;     ...
;     PG8_STAGE(PG8_SB(0, 0), cB, voffB); PG8_STAGE(PG8_SB(0, 1), cB + hstepB, voffB); PG8_STAGE(PG8_SA(0, 0), cA, voffA); PG8_STAGE(PG8_SA(0, 1), cA + hstepA, voffA);
;     if (wr == 1) PG8_BAR;
;     PG8_WAIT_V(2); PG8_BAR;
;     PG8_STAGE(PG8_SB(1, 0), cB + kstep, voffB); PG8_STAGE(PG8_SA(1, 0), cA + kstep, voffA); PG8_STAGE(PG8_SB(1, 1), cB + hstepB + kstep, voffB);
;     PG8_WAIT_V(6); PG8_BAR;
.LBB0_474:
	v_readlane_b32 s6, v250, 2
	v_readlane_b32 s7, v250, 3
	v_readlane_b32 s16, v252, 4
	s_lshl_b64 s[6:7], s[6:7], 12
	v_readlane_b32 s28, v252, 16
	v_bfe_u32 v180, v10, 4, 2
	v_readlane_b32 s22, v252, 10
	v_readlane_b32 s29, v252, 17
	s_add_u32 s44, s28, s6
	v_and_b32_e32 v1, 15, v10
	v_lshlrev_b32_e32 v11, 4, v180
	v_lshlrev_b32_e32 v10, 2, v10
	s_addc_u32 s45, s29, s7
	s_lshl_b32 s22, s4, 6
	v_lshl_or_b32 v11, v1, 6, v11
	s_lshl_b32 s4, s4, 13
	v_and_b32_e32 v10, 32, v10
	v_readlane_b32 s23, v252, 11
	v_bitop3_b32 v12, v11, s4, v10 bitop3:0xde
	s_lshl_b32 s4, s5, 5
	v_readlane_b32 s24, v252, 12
	v_readlane_b32 s25, v252, 13
	s_and_b32 s23, s4, 0x60
	s_add_i32 m0, s59, 0x18000
	v_lshl_add_u64 v[8:9], v[8:9], 0, s[60:61]
	s_lshl_b32 s4, s23, 7
	s_nop 0
	global_load_lds_dwordx4 v[8:9], off
	v_lshl_add_u64 v[6:7], v[6:7], 0, s[60:61]
	s_add_i32 m0, s59, 0x1a000
	s_add_i32 s24, s59, 0x8000
	s_add_i32 s25, s59, 0xa000
	v_bitop3_b32 v181, v11, s4, v10 bitop3:0xde
	global_load_lds_dwordx4 v[6:7], off
	v_lshl_add_u64 v[2:3], v[2:3], 0, s[60:61]
	s_mov_b32 m0, s24
	s_add_u32 s4, s94, 0x10080
	global_load_lds_dwordx4 v[2:3], off
	v_lshl_add_u64 v[2:3], v[4:5], 0, s[60:61]
	s_mov_b32 m0, s25
	s_addc_u32 s5, s95, 0
	global_load_lds_dwordx4 v[2:3], off
	s_add_i32 m0, s59, 0x1c000
	v_lshl_add_u64 v[2:3], s[4:5], 0, v[160:161]
	global_load_lds_dwordx4 v[2:3], off
	v_lshl_add_u64 v[2:3], s[4:5], 0, v[170:171]
	s_add_i32 m0, s59, 0x1e000
	v_readlane_b32 s17, v252, 5
	global_load_lds_dwordx4 v[2:3], off
	s_waitcnt vmcnt(6)
	s_cmpk_lt_u32 s8, 0x100
	v_readlane_b32 s16, v251, 5
	s_mov_b32 s56, 0
	s_cselect_b64 s[46:47], -1, 0
	v_add_u32_e32 v182, 0, v12
	v_readlane_b32 s17, v251, 6
	v_readlane_b32 s18, v252, 6
	v_readlane_b32 s19, v252, 7
	v_readlane_b32 s20, v252, 8
	v_readlane_b32 s21, v252, 9
	v_readlane_b32 s26, v252, 14
	v_readlane_b32 s27, v252, 15
	v_readlane_b32 s30, v252, 18
	v_readlane_b32 s31, v252, 19
	s_barrier
	v_readfirstlane_b32 s98, v188
	s_cmp_lt_u32 s98, 0x100
	s_cbranch_scc1 .Lfill_skip2
	s_barrier

; #define PG8_STAGE(bufoff, gbase, voff) do { _Pragma("unroll") for (int _i = 0; _i < 2; ++_i) \
;         __builtin_amdgcn_global_load_lds((const unsigned*)((const char*)(gbase) + (voff)[_i]), (LAS unsigned*)(lds + (bufoff) + ldsw + _i * 8192), 16, 0, 0); } while (0)
; #define PG8_WAIT_V(n) asm volatile("s_waitcnt vmcnt(" #n ")" ::: "memory")
; #define PG8_BAR __builtin_amdgcn_s_barrier()
; template <class Epi, class Order = StaticOrder, bool HALFN = false>
; __device__ __forceinline__ void gemm_phase(LAS unsigned char* lds, const Gemm g, const Epi& E) {
;     ...
;     for (int i = 0; i < 2; ++i) { int R, C; stage_rc(tid * 16 + i * 8192, R, C); const int Rb = (R & ~31) + perm32(R & 31);
;         voffA[i] = (unsigned)(R * g.lda + C) * 2u; voffB[i] = (unsigned)(Rb * g.ldb + C) * 2u; }
;     const size_t kstep = (size_t)(BK * 2);
;     const size_t hstepA = (size_t)HALF * g.lda * 2, hstepB = (size_t)HALF * g.ldb * 2;
;     const size_t tstepA = 2 * hstepA, tstepB = 2 * hstepB;
;     const unsigned ldsw = (unsigned)wid * 1024u;
;     const int aoff = lds_byte(wr * 64 + fr, fq * 8), boff = lds_byte(wc * 32 + fr, fq * 8);
;     ...
;     PG8_STAGE(PG8_SB(0, 0), cB, voffB); PG8_STAGE(PG8_SB(0, 1), cB + hstepB, voffB); PG8_STAGE(PG8_SA(0, 0), cA, voffA); PG8_STAGE(PG8_SA(0, 1), cA + hstepA, voffA);
;     if (wr == 1) PG8_BAR;
;     PG8_WAIT_V(2); PG8_BAR;
;     PG8_STAGE(PG8_SB(1, 0), cB + kstep, voffB); PG8_STAGE(PG8_SA(1, 0), cA + kstep, voffA); PG8_STAGE(PG8_SB(1, 1), cB + hstepB + kstep, voffB);
;     PG8_WAIT_V(6); PG8_BAR;
.LBB0_504:
	s_lshl_b64 s[6:7], s[78:79], 25
	v_readlane_b32 s9, v251, 21
	v_bfe_u32 v138, v10, 4, 2
	s_add_u32 s44, s9, s6
	v_readlane_b32 s6, v251, 22
	v_and_b32_e32 v1, 15, v10
	v_lshlrev_b32_e32 v11, 4, v138
	v_lshlrev_b32_e32 v10, 2, v10
	s_addc_u32 s45, s6, s7
	s_lshl_b32 s24, s4, 6
	v_lshl_or_b32 v11, v1, 6, v11
	s_lshl_b32 s4, s4, 13
	v_and_b32_e32 v10, 32, v10
	v_bitop3_b32 v12, v11, s4, v10 bitop3:0xde
	s_lshl_b32 s4, s5, 5
	s_and_b32 s25, s4, 0x60
	s_add_i32 m0, s59, 0x18000
	v_lshl_add_u64 v[8:9], v[8:9], 0, s[60:61]
	s_lshl_b32 s4, s25, 7
	s_nop 0
	global_load_lds_dwordx4 v[8:9], off
	v_lshl_add_u64 v[6:7], v[6:7], 0, s[60:61]
	s_add_i32 m0, s59, 0x1a000
	s_add_i32 s47, s59, 0x8000
	s_add_i32 s89, s59, 0xa000
	v_bitop3_b32 v139, v11, s4, v10 bitop3:0xde
	global_load_lds_dwordx4 v[6:7], off
	v_lshl_add_u64 v[2:3], v[2:3], 0, s[60:61]
	s_mov_b32 m0, s47
	s_add_u32 s4, s54, 0x10080
	global_load_lds_dwordx4 v[2:3], off
	v_lshl_add_u64 v[2:3], v[4:5], 0, s[60:61]
	s_mov_b32 m0, s89
	s_addc_u32 s5, s55, 0
	global_load_lds_dwordx4 v[2:3], off
	s_add_i32 m0, s59, 0x1c000
	v_lshl_add_u64 v[2:3], s[4:5], 0, v[132:133]
	global_load_lds_dwordx4 v[2:3], off
	v_lshl_add_u64 v[2:3], s[4:5], 0, v[136:137]
	s_add_i32 m0, s59, 0x1e000
	s_cmpk_lt_u32 s8, 0x100
	global_load_lds_dwordx4 v[2:3], off
	s_waitcnt vmcnt(6)
	s_mov_b32 s26, 0
	s_cselect_b64 s[48:49], -1, 0
	v_add_u32_e32 v140, 0, v12
	s_barrier
	v_readfirstlane_b32 s98, v188
	s_cmp_lt_u32 s98, 0x100
	s_cbranch_scc1 .Lfill_skip3
	s_barrier

; #define PG8_STAGE(bufoff, gbase, voff) do { _Pragma("unroll") for (int _i = 0; _i < 2; ++_i) \
;         __builtin_amdgcn_global_load_lds((const unsigned*)((const char*)(gbase) + (voff)[_i]), (LAS unsigned*)(lds + (bufoff) + ldsw + _i * 8192), 16, 0, 0); } while (0)
; #define PG8_WAIT_V(n) asm volatile("s_waitcnt vmcnt(" #n ")" ::: "memory")
; #define PG8_BAR __builtin_amdgcn_s_barrier()
; template <class Epi, class Order = StaticOrder, bool HALFN = false>
; __device__ __forceinline__ void gemm_phase(LAS unsigned char* lds, const Gemm g, const Epi& E) {
;     ...
;     for (int i = 0; i < 2; ++i) { int R, C; stage_rc(tid * 16 + i * 8192, R, C); const int Rb = (R & ~31) + perm32(R & 31);
;         voffA[i] = (unsigned)(R * g.lda + C) * 2u; voffB[i] = (unsigned)(Rb * g.ldb + C) * 2u; }
;     const size_t kstep = (size_t)(BK * 2);
;     const size_t hstepA = (size_t)HALF * g.lda * 2, hstepB = (size_t)HALF * g.ldb * 2;
;     const size_t tstepA = 2 * hstepA, tstepB = 2 * hstepB;
;     const unsigned ldsw = (unsigned)wid * 1024u;
;     const int aoff = lds_byte(wr * 64 + fr, fq * 8), boff = lds_byte(wc * 32 + fr, fq * 8);
;     ...
;     PG8_STAGE(PG8_SB(0, 0), cB, voffB); PG8_STAGE(PG8_SB(0, 1), cB + hstepB, voffB); PG8_STAGE(PG8_SA(0, 0), cA, voffA); PG8_STAGE(PG8_SA(0, 1), cA + hstepA, voffA);
;     if (wr == 1) PG8_BAR;
;     PG8_WAIT_V(2); PG8_BAR;
;     PG8_STAGE(PG8_SB(1, 0), cB + kstep, voffB); PG8_STAGE(PG8_SA(1, 0), cA + kstep, voffA); PG8_STAGE(PG8_SB(1, 1), cB + hstepB + kstep, voffB);
;     PG8_WAIT_V(6); PG8_BAR;
.LBB0_595:
	v_bfe_u32 v181, v15, 4, 2
	v_and_b32_e32 v180, 15, v15
	v_lshlrev_b32_e32 v18, 4, v181
	v_lshlrev_b32_e32 v15, 2, v15
	s_lshl_b32 s20, s4, 6
	v_lshl_or_b32 v18, v180, 6, v18
	s_lshl_b32 s4, s4, 13
	v_and_b32_e32 v15, 32, v15
	v_bitop3_b32 v19, v18, s4, v15 bitop3:0xde
	s_lshl_b32 s4, s5, 5
	s_and_b32 s21, s4, 0x60
	s_add_i32 m0, s16, 0x18000
	v_lshl_add_u64 v[8:9], v[8:9], 0, s[60:61]
	s_lshl_b32 s4, s21, 7
	s_nop 0
	global_load_lds_dwordx4 v[8:9], off
	v_lshl_add_u64 v[6:7], v[6:7], 0, s[60:61]
	s_add_i32 m0, s16, 0x1a000
	s_add_i32 s22, s16, 0x8000
	s_add_i32 s23, s16, 0xa000
	v_bitop3_b32 v182, v18, s4, v15 bitop3:0xde
	global_load_lds_dwordx4 v[6:7], off
	v_lshl_add_u64 v[2:3], v[2:3], 0, s[60:61]
	s_mov_b32 m0, s22
	s_add_u32 s4, s54, 0xc0080
	global_load_lds_dwordx4 v[2:3], off
	v_lshl_add_u64 v[2:3], v[4:5], 0, s[60:61]
	s_mov_b32 m0, s23
	s_addc_u32 s5, s55, 0
	global_load_lds_dwordx4 v[2:3], off
	s_add_i32 m0, s16, 0x1c000
	v_lshl_add_u64 v[2:3], s[4:5], 0, v[134:135]
	global_load_lds_dwordx4 v[2:3], off
	v_lshl_add_u64 v[2:3], s[4:5], 0, v[138:139]
	s_add_i32 m0, s16, 0x1e000
	s_movk_i32 s7, 0xc00
	global_load_lds_dwordx4 v[2:3], off
	v_lshrrev_b32_e32 v1, 1, v1
	v_mul_lo_u32 v2, v11, s7
	s_mov_b32 s6, 0xc000
	v_mad_u64_u32 v[2:3], s[4:5], v1, s6, v[2:3]
	v_or_b32_e32 v1, v2, v10
	v_add_lshl_u32 v140, v1, v12, 1
	v_lshrrev_b32_e32 v1, 1, v13
	v_mul_lo_u32 v2, v16, s7
	s_waitcnt vmcnt(6)
	v_mad_u64_u32 v[2:3], s[4:5], v1, s6, v[2:3]
	s_cmpk_lt_u32 s8, 0x100
	v_or_b32_e32 v1, v2, v14
	s_cselect_b64 s[46:47], -1, 0
	v_mov_b32_e32 v141, v0
	v_add_lshl_u32 v142, v1, v17, 1
	v_mov_b32_e32 v143, v0
	s_mov_b32 s24, 0
	v_add_u32_e32 v183, 0, v19
	s_barrier
	v_readfirstlane_b32 s98, v188
	s_cmp_lt_u32 s98, 0x100
	s_cbranch_scc1 .Lfill_skip4
	s_barrier

; __device__ __forceinline__ void unpack8(u32x4 g, f32x4& a, f32x4& b) { a = (f32x4){bf_lo(g.x), bf_hi(g.x), bf_lo(g.y), bf_hi(g.y)}; b = (f32x4){bf_lo(g.z), bf_hi(g.z), bf_lo(g.w), bf_hi(g.w)}; }
; #define PG8_STAGE(bufoff, gbase, voff) do { _Pragma("unroll") for (int _i = 0; _i < 2; ++_i) \
;         __builtin_amdgcn_global_load_lds((const unsigned*)((const char*)(gbase) + (voff)[_i]), (LAS unsigned*)(lds + (bufoff) + ldsw + _i * 8192), 16, 0, 0); } while (0)
; #define PG8_WAIT_V(n) asm volatile("s_waitcnt vmcnt(" #n ")" ::: "memory")
; #define PG8_BAR __builtin_amdgcn_s_barrier()
; #define EPI_OPAQUE asm volatile("" : "+v"(fr), "+v"(fq));
; template <class Epi, class Order = StaticOrder, bool HALFN = false>
; __device__ __forceinline__ void gemm_phase(LAS unsigned char* lds, const Gemm g, const Epi& E) {
;     ...
;     PG8_STAGE(PG8_SB(0, 0), cB, voffB); PG8_STAGE(PG8_SB(0, 1), cB + hstepB, voffB); PG8_STAGE(PG8_SA(0, 0), cA, voffA); PG8_STAGE(PG8_SA(0, 1), cA + hstepA, voffA);
;     if (wr == 1) PG8_BAR;
;     PG8_WAIT_V(2); PG8_BAR;
;     PG8_STAGE(PG8_SB(1, 0), cB + kstep, voffB); PG8_STAGE(PG8_SA(1, 0), cA + kstep, voffA); PG8_STAGE(PG8_SB(1, 1), cB + hstepB + kstep, voffB);
;     PG8_WAIT_V(6); PG8_BAR;
;     __device__ __forceinline__ void init(f32x4 (&acc)[2][2][4][2], const Unit& u, int wr, int wc, int fr, int fq) const {
;         EPI_OPAQUE
;         if (basef) {
;             EPI_ROWS_BEGIN EPI_COLS_BEGIN
;                 const size_t off = (size_t)row * DM + col;
;                 acc[ai][bj][m][0] = *(const f32x4*)(basef + off); acc[ai][bj][m][1] = *(const f32x4*)(basef + off + 4);
;             EPI_END EPI_END
;         } else {
;             EPI_ROWS_BEGIN EPI_COLS_BEGIN
;                 unpack8(*(const u32x4*)(baseb + (size_t)row * DM + col), acc[ai][bj][m][0], acc[ai][bj][m][1]);
;             EPI_END EPI_END
.LBB0_694:
	v_mov_b32_e32 v133, v0
	v_lshl_add_u64 v[82:83], s[80:81], 0, v[132:133]
	v_mov_b32_e32 v137, v0
	v_lshl_add_u64 v[84:85], s[80:81], 0, v[136:137]
	v_mov_b32_e32 v131, v0
	s_add_i32 m0, s16, 0x18000
	v_lshl_add_u64 v[82:83], v[82:83], 0, s[60:61]
	v_lshl_add_u64 v[102:103], s[62:63], 0, v[130:131]
	v_mov_b32_e32 v135, v0
	s_lshl_b32 s6, s4, 13
	s_lshl_b32 s7, s15, 7
	s_nop 0
	global_load_lds_dwordx4 v[82:83], off
	v_lshl_add_u64 v[82:83], v[84:85], 0, s[60:61]
	s_add_i32 m0, s16, 0x1a000
	s_add_i32 s20, s16, 0x8000
	s_add_i32 s21, s16, 0xa000
	v_lshl_add_u64 v[104:105], s[62:63], 0, v[134:135]
	global_load_lds_dwordx4 v[82:83], off
	v_lshl_add_u64 v[82:83], v[102:103], 0, s[60:61]
	s_mov_b32 m0, s20
	s_add_u32 s4, s80, 0x80080
	global_load_lds_dwordx4 v[82:83], off
	v_lshl_add_u64 v[82:83], v[104:105], 0, s[60:61]
	s_mov_b32 m0, s21
	s_addc_u32 s5, s81, 0
	global_load_lds_dwordx4 v[82:83], off
	s_add_i32 m0, s16, 0x1c000
	v_lshl_add_u64 v[82:83], s[4:5], 0, v[132:133]
	global_load_lds_dwordx4 v[82:83], off
	v_lshl_add_u64 v[82:83], s[4:5], 0, v[136:137]
	s_add_i32 m0, s16, 0x1e000
	v_or_b32_e32 v143, s11, v1
	global_load_lds_dwordx4 v[82:83], off
	v_lshlrev_b32_e32 v146, 4, v142
	v_lshlrev_b32_e32 v147, 6, v143
	s_movk_i32 s4, 0x3c0
	v_lshlrev_b32_e32 v143, 2, v143
	v_and_or_b32 v147, v147, s4, v146
	v_and_b32_e32 v143, 32, v143
	v_bitop3_b32 v147, v147, s6, v143 bitop3:0xde
	v_lshl_or_b32 v143, v1, 6, v146
	v_lshlrev_b32_e32 v146, 2, v1
	v_and_b32_e32 v146, 32, v146
	v_bitop3_b32 v143, v143, s7, v146 bitop3:0xde
	v_lshlrev_b32_e32 v146, 15, v138
	v_and_b32_e32 v146, 0xffff0000, v146
	v_lshl_add_u32 v139, v139, 12, v146
	v_and_b32_e32 v138, 1, v138
	v_lshl_or_b32 v138, v138, 6, v139
	v_lshl_add_u32 v138, v140, 1, v138
	v_lshlrev_b32_e32 v140, 15, v141
	v_and_b32_e32 v140, 0xffff0000, v140
	s_waitcnt vmcnt(6)
	v_lshl_add_u32 v140, v144, 12, v140
	v_and_b32_e32 v141, 1, v141
	s_cmpk_lt_u32 s22, 0x100
	v_lshl_or_b32 v140, v141, 6, v140
	s_waitcnt vmcnt(0)
	v_lshlrev_b32_e32 v2, 16, v6
	v_and_b32_e32 v3, 0xffff0000, v6
	v_lshlrev_b32_e32 v4, 16, v7
	v_and_b32_e32 v5, 0xffff0000, v7
	v_lshlrev_b32_e32 v6, 16, v8
	v_and_b32_e32 v7, 0xffff0000, v8
	v_lshlrev_b32_e32 v8, 16, v9
	v_and_b32_e32 v9, 0xffff0000, v9
	v_lshlrev_b32_e32 v22, 16, v10
	v_and_b32_e32 v23, 0xffff0000, v10
	v_lshlrev_b32_e32 v24, 16, v11
	v_and_b32_e32 v25, 0xffff0000, v11
	v_lshlrev_b32_e32 v34, 16, v12
	v_and_b32_e32 v35, 0xffff0000, v12
	v_lshlrev_b32_e32 v36, 16, v13
	v_and_b32_e32 v37, 0xffff0000, v13
	v_lshlrev_b32_e32 v10, 16, v14
	v_and_b32_e32 v11, 0xffff0000, v14
	v_lshlrev_b32_e32 v12, 16, v15
	v_and_b32_e32 v13, 0xffff0000, v15
	v_lshlrev_b32_e32 v14, 16, v16
	v_and_b32_e32 v15, 0xffff0000, v16
	v_lshlrev_b32_e32 v16, 16, v17
	v_and_b32_e32 v17, 0xffff0000, v17
	v_lshlrev_b32_e32 v38, 16, v18
	v_and_b32_e32 v39, 0xffff0000, v18
	v_lshlrev_b32_e32 v40, 16, v19
	v_and_b32_e32 v41, 0xffff0000, v19
	v_lshlrev_b32_e32 v46, 16, v20
	v_and_b32_e32 v47, 0xffff0000, v20
	v_lshlrev_b32_e32 v48, 16, v21
	v_and_b32_e32 v49, 0xffff0000, v21
	v_lshlrev_b32_e32 v18, 16, v26
	v_and_b32_e32 v19, 0xffff0000, v26
	v_lshlrev_b32_e32 v20, 16, v27
	v_and_b32_e32 v21, 0xffff0000, v27
	v_lshlrev_b32_e32 v26, 16, v28
	v_and_b32_e32 v27, 0xffff0000, v28
	v_lshlrev_b32_e32 v28, 16, v29
	v_and_b32_e32 v29, 0xffff0000, v29
	v_lshlrev_b32_e32 v50, 16, v30
	v_and_b32_e32 v51, 0xffff0000, v30
	v_lshlrev_b32_e32 v52, 16, v31
	v_and_b32_e32 v53, 0xffff0000, v31
	v_lshlrev_b32_e32 v54, 16, v32
	v_and_b32_e32 v55, 0xffff0000, v32
	v_lshlrev_b32_e32 v56, 16, v33
	v_and_b32_e32 v57, 0xffff0000, v33
	v_lshlrev_b32_e32 v30, 16, v42
	v_and_b32_e32 v31, 0xffff0000, v42
	v_lshlrev_b32_e32 v32, 16, v43
	v_and_b32_e32 v33, 0xffff0000, v43
	v_lshlrev_b32_e32 v42, 16, v44
	v_and_b32_e32 v43, 0xffff0000, v44
	v_lshlrev_b32_e32 v44, 16, v45
	v_and_b32_e32 v45, 0xffff0000, v45
	v_lshlrev_b32_e32 v58, 16, v60
	v_and_b32_e32 v59, 0xffff0000, v60
	v_lshlrev_b32_e32 v60, 16, v61
	v_and_b32_e32 v61, 0xffff0000, v61
	v_lshlrev_b32_e32 v66, 16, v62
	v_and_b32_e32 v67, 0xffff0000, v62
	v_lshlrev_b32_e32 v68, 16, v63
	v_and_b32_e32 v69, 0xffff0000, v63
	v_lshlrev_b32_e32 v62, 16, v70
	v_and_b32_e32 v63, 0xffff0000, v70
	v_lshlrev_b32_e32 v64, 16, v71
	v_and_b32_e32 v65, 0xffff0000, v71
	v_lshlrev_b32_e32 v70, 16, v72
	v_and_b32_e32 v71, 0xffff0000, v72
	v_lshlrev_b32_e32 v72, 16, v73
	v_and_b32_e32 v73, 0xffff0000, v73
	v_lshlrev_b32_e32 v74, 16, v78
	v_and_b32_e32 v75, 0xffff0000, v78
	v_lshlrev_b32_e32 v76, 16, v79
	v_and_b32_e32 v77, 0xffff0000, v79
	v_lshlrev_b32_e32 v78, 16, v80
	v_and_b32_e32 v79, 0xffff0000, v80
	v_lshlrev_b32_e32 v80, 16, v81
	v_and_b32_e32 v81, 0xffff0000, v81
	v_lshlrev_b32_e32 v82, 16, v86
	v_and_b32_e32 v83, 0xffff0000, v86
	v_lshlrev_b32_e32 v84, 16, v87
	v_and_b32_e32 v85, 0xffff0000, v87
	v_lshlrev_b32_e32 v86, 16, v88
	v_and_b32_e32 v87, 0xffff0000, v88
	v_lshlrev_b32_e32 v88, 16, v89
	v_and_b32_e32 v89, 0xffff0000, v89
	v_lshlrev_b32_e32 v102, 16, v90
	v_and_b32_e32 v103, 0xffff0000, v90
	v_lshlrev_b32_e32 v104, 16, v91
	v_and_b32_e32 v105, 0xffff0000, v91
	v_lshlrev_b32_e32 v110, 16, v92
	v_and_b32_e32 v111, 0xffff0000, v92
	v_lshlrev_b32_e32 v112, 16, v93
	v_and_b32_e32 v113, 0xffff0000, v93
	v_lshlrev_b32_e32 v90, 16, v94
	v_and_b32_e32 v91, 0xffff0000, v94
	v_lshlrev_b32_e32 v92, 16, v95
	v_and_b32_e32 v93, 0xffff0000, v95
	v_lshlrev_b32_e32 v94, 16, v96
	v_and_b32_e32 v95, 0xffff0000, v96
	v_lshlrev_b32_e32 v96, 16, v97
	v_and_b32_e32 v97, 0xffff0000, v97
	v_lshlrev_b32_e32 v114, 16, v98
	v_and_b32_e32 v115, 0xffff0000, v98
	v_lshlrev_b32_e32 v116, 16, v99
	v_and_b32_e32 v117, 0xffff0000, v99
	v_lshlrev_b32_e32 v118, 16, v100
	v_and_b32_e32 v119, 0xffff0000, v100
	v_lshlrev_b32_e32 v120, 16, v101
	v_and_b32_e32 v121, 0xffff0000, v101
	v_lshlrev_b32_e32 v98, 16, v106
	v_and_b32_e32 v99, 0xffff0000, v106
	v_lshlrev_b32_e32 v100, 16, v107
	v_and_b32_e32 v101, 0xffff0000, v107
	v_lshlrev_b32_e32 v106, 16, v108
	v_and_b32_e32 v107, 0xffff0000, v108
	v_lshlrev_b32_e32 v108, 16, v109
	v_and_b32_e32 v109, 0xffff0000, v109
	v_lshlrev_b32_e32 v122, 16, v126
	v_and_b32_e32 v123, 0xffff0000, v126
	v_lshlrev_b32_e32 v124, 16, v127
	v_and_b32_e32 v125, 0xffff0000, v127
	v_lshlrev_b32_e32 v126, 16, v128
	v_and_b32_e32 v127, 0xffff0000, v128
	v_lshlrev_b32_e32 v128, 16, v129
	v_and_b32_e32 v129, 0xffff0000, v129
	s_cselect_b64 s[44:45], -1, 0
	v_mov_b32_e32 v139, v0
	v_lshl_add_u32 v140, v145, 1, v140
	v_mov_b32_e32 v141, v0
	s_mov_b32 s22, 0
	v_add_u32_e32 v144, 0, v147
	s_barrier
	v_readfirstlane_b32 s98, v188
	s_cmp_lt_u32 s98, 0x100
	s_cbranch_scc1 .Lfill_skip5
	s_barrier
; __device__ __forceinline__ void unpack8(u32x4 g, f32x4& a, f32x4& b) { a = (f32x4){bf_lo(g.x), bf_hi(g.x), bf_lo(g.y), bf_hi(g.y)}; b = (f32x4){bf_lo(g.z), bf_hi(g.z), bf_lo(g.w), bf_hi(g.w)}; }
;     __device__ __forceinline__ void init(f32x4 (&acc)[2][2][4][2], const Unit& u, int wr, int wc, int fr, int fq) const {
;     ...
;             EPI_ROWS_BEGIN EPI_COLS_BEGIN
;                 const size_t off = (size_t)row * DM + col;
;                 acc[ai][bj][m][0] = *(const f32x4*)(basef + off); acc[ai][bj][m][1] = *(const f32x4*)(basef + off + 4);
;             EPI_END EPI_END
;         } else {
;             EPI_ROWS_BEGIN EPI_COLS_BEGIN
;                 unpack8(*(const u32x4*)(baseb + (size_t)row * DM + col), acc[ai][bj][m][0], acc[ai][bj][m][1]);
;             EPI_END EPI_END
.Lfill_skip5:
	s_branch .LBB0_697
.LBB0_695:
	s_waitcnt vmcnt(0)
	v_lshlrev_b32_e32 v2, 16, v6
	v_and_b32_e32 v3, 0xffff0000, v6
	v_lshlrev_b32_e32 v4, 16, v7
	v_and_b32_e32 v5, 0xffff0000, v7
	v_lshlrev_b32_e32 v6, 16, v8
	v_and_b32_e32 v7, 0xffff0000, v8
	v_lshlrev_b32_e32 v8, 16, v9
	v_and_b32_e32 v9, 0xffff0000, v9
	v_lshlrev_b32_e32 v22, 16, v10
	v_and_b32_e32 v23, 0xffff0000, v10
	v_lshlrev_b32_e32 v24, 16, v11
	v_and_b32_e32 v25, 0xffff0000, v11
	v_lshlrev_b32_e32 v34, 16, v12
	v_and_b32_e32 v35, 0xffff0000, v12
	v_lshlrev_b32_e32 v36, 16, v13
	v_and_b32_e32 v37, 0xffff0000, v13
	v_lshlrev_b32_e32 v10, 16, v14
	v_and_b32_e32 v11, 0xffff0000, v14
	v_lshlrev_b32_e32 v12, 16, v15
	v_and_b32_e32 v13, 0xffff0000, v15
	v_lshlrev_b32_e32 v14, 16, v16
	v_and_b32_e32 v15, 0xffff0000, v16
	v_lshlrev_b32_e32 v16, 16, v17
	v_and_b32_e32 v17, 0xffff0000, v17
	v_lshlrev_b32_e32 v38, 16, v18
	v_and_b32_e32 v39, 0xffff0000, v18
	v_lshlrev_b32_e32 v40, 16, v19
	v_and_b32_e32 v41, 0xffff0000, v19
	v_lshlrev_b32_e32 v46, 16, v20
	v_and_b32_e32 v47, 0xffff0000, v20
	v_lshlrev_b32_e32 v48, 16, v21
	v_and_b32_e32 v49, 0xffff0000, v21
	v_lshlrev_b32_e32 v18, 16, v26
	v_and_b32_e32 v19, 0xffff0000, v26
	v_lshlrev_b32_e32 v20, 16, v27
	v_and_b32_e32 v21, 0xffff0000, v27
	v_lshlrev_b32_e32 v26, 16, v28
	v_and_b32_e32 v27, 0xffff0000, v28
	v_lshlrev_b32_e32 v28, 16, v29
	v_and_b32_e32 v29, 0xffff0000, v29
	v_lshlrev_b32_e32 v50, 16, v30
	v_and_b32_e32 v51, 0xffff0000, v30
	v_lshlrev_b32_e32 v52, 16, v31
	v_and_b32_e32 v53, 0xffff0000, v31
	v_lshlrev_b32_e32 v54, 16, v32
	v_and_b32_e32 v55, 0xffff0000, v32
	v_lshlrev_b32_e32 v56, 16, v33
	v_and_b32_e32 v57, 0xffff0000, v33
	v_lshlrev_b32_e32 v30, 16, v42
	v_and_b32_e32 v31, 0xffff0000, v42
	v_lshlrev_b32_e32 v32, 16, v43
	v_and_b32_e32 v33, 0xffff0000, v43
	v_lshlrev_b32_e32 v42, 16, v44
	v_and_b32_e32 v43, 0xffff0000, v44
	v_lshlrev_b32_e32 v44, 16, v45
	v_and_b32_e32 v45, 0xffff0000, v45
	v_lshlrev_b32_e32 v58, 16, v60
	v_and_b32_e32 v59, 0xffff0000, v60
	v_lshlrev_b32_e32 v60, 16, v61
	v_and_b32_e32 v61, 0xffff0000, v61
	v_lshlrev_b32_e32 v66, 16, v62
	v_and_b32_e32 v67, 0xffff0000, v62
	v_lshlrev_b32_e32 v68, 16, v63
	v_and_b32_e32 v69, 0xffff0000, v63
	v_lshlrev_b32_e32 v62, 16, v70
	v_and_b32_e32 v63, 0xffff0000, v70
	v_lshlrev_b32_e32 v64, 16, v71
	v_and_b32_e32 v65, 0xffff0000, v71
	v_lshlrev_b32_e32 v70, 16, v72
	v_and_b32_e32 v71, 0xffff0000, v72
	v_lshlrev_b32_e32 v72, 16, v73
	v_and_b32_e32 v73, 0xffff0000, v73
	v_lshlrev_b32_e32 v74, 16, v78
	v_and_b32_e32 v75, 0xffff0000, v78
	v_lshlrev_b32_e32 v76, 16, v79
	v_and_b32_e32 v77, 0xffff0000, v79
	v_lshlrev_b32_e32 v78, 16, v80
	v_and_b32_e32 v79, 0xffff0000, v80
	v_lshlrev_b32_e32 v80, 16, v81
	v_and_b32_e32 v81, 0xffff0000, v81
	v_lshlrev_b32_e32 v82, 16, v86
	v_and_b32_e32 v83, 0xffff0000, v86
	v_lshlrev_b32_e32 v84, 16, v87
	v_and_b32_e32 v85, 0xffff0000, v87
	v_lshlrev_b32_e32 v86, 16, v88
	v_and_b32_e32 v87, 0xffff0000, v88
	v_lshlrev_b32_e32 v88, 16, v89
	v_and_b32_e32 v89, 0xffff0000, v89
	v_lshlrev_b32_e32 v102, 16, v90
	v_and_b32_e32 v103, 0xffff0000, v90
	v_lshlrev_b32_e32 v104, 16, v91
	v_and_b32_e32 v105, 0xffff0000, v91
	v_lshlrev_b32_e32 v110, 16, v92
	v_and_b32_e32 v111, 0xffff0000, v92
	v_lshlrev_b32_e32 v112, 16, v93
	v_and_b32_e32 v113, 0xffff0000, v93
	v_lshlrev_b32_e32 v90, 16, v94
	v_and_b32_e32 v91, 0xffff0000, v94
	v_lshlrev_b32_e32 v92, 16, v95
	v_and_b32_e32 v93, 0xffff0000, v95
	v_lshlrev_b32_e32 v94, 16, v96
	v_and_b32_e32 v95, 0xffff0000, v96
	v_lshlrev_b32_e32 v96, 16, v97
	v_and_b32_e32 v97, 0xffff0000, v97
	v_lshlrev_b32_e32 v114, 16, v98
	v_and_b32_e32 v115, 0xffff0000, v98
	v_lshlrev_b32_e32 v116, 16, v99
	v_and_b32_e32 v117, 0xffff0000, v99
	v_lshlrev_b32_e32 v118, 16, v100
	v_and_b32_e32 v119, 0xffff0000, v100
	v_lshlrev_b32_e32 v120, 16, v101
	v_and_b32_e32 v121, 0xffff0000, v101
	v_lshlrev_b32_e32 v98, 16, v106
	v_and_b32_e32 v99, 0xffff0000, v106
	v_lshlrev_b32_e32 v100, 16, v107
	v_and_b32_e32 v101, 0xffff0000, v107
	v_lshlrev_b32_e32 v106, 16, v108
	v_and_b32_e32 v107, 0xffff0000, v108
	v_lshlrev_b32_e32 v108, 16, v109
	v_and_b32_e32 v109, 0xffff0000, v109
	v_lshlrev_b32_e32 v122, 16, v126
	v_and_b32_e32 v123, 0xffff0000, v126
	v_lshlrev_b32_e32 v124, 16, v127
	v_and_b32_e32 v125, 0xffff0000, v127
	v_lshlrev_b32_e32 v126, 16, v128
	v_and_b32_e32 v127, 0xffff0000, v128
	v_lshlrev_b32_e32 v128, 16, v129
	v_and_b32_e32 v129, 0xffff0000, v129
	s_mov_b64 s[4:5], 0

; #define PG8_STAGE(bufoff, gbase, voff) do { _Pragma("unroll") for (int _i = 0; _i < 2; ++_i) \
;         __builtin_amdgcn_global_load_lds((const unsigned*)((const char*)(gbase) + (voff)[_i]), (LAS unsigned*)(lds + (bufoff) + ldsw + _i * 8192), 16, 0, 0); } while (0)
; #define PG8_WAIT_V(n) asm volatile("s_waitcnt vmcnt(" #n ")" ::: "memory")
; #define PG8_BAR __builtin_amdgcn_s_barrier()
; template <class Epi, class Order = StaticOrder, bool HALFN = false>
; __device__ __forceinline__ void gemm_phase(LAS unsigned char* lds, const Gemm g, const Epi& E) {
;     ...
;     for (int i = 0; i < 2; ++i) { int R, C; stage_rc(tid * 16 + i * 8192, R, C); const int Rb = (R & ~31) + perm32(R & 31);
;         voffA[i] = (unsigned)(R * g.lda + C) * 2u; voffB[i] = (unsigned)(Rb * g.ldb + C) * 2u; }
;     const size_t kstep = (size_t)(BK * 2);
;     const size_t hstepA = (size_t)HALF * g.lda * 2, hstepB = (size_t)HALF * g.ldb * 2;
;     const size_t tstepA = 2 * hstepA, tstepB = 2 * hstepB;
;     const unsigned ldsw = (unsigned)wid * 1024u;
;     const int aoff = lds_byte(wr * 64 + fr, fq * 8), boff = lds_byte(wc * 32 + fr, fq * 8);
;     ...
;     PG8_STAGE(PG8_SB(0, 0), cB, voffB); PG8_STAGE(PG8_SB(0, 1), cB + hstepB, voffB); PG8_STAGE(PG8_SA(0, 0), cA, voffA); PG8_STAGE(PG8_SA(0, 1), cA + hstepA, voffA);
;     if (wr == 1) PG8_BAR;
;     PG8_WAIT_V(2); PG8_BAR;
;     PG8_STAGE(PG8_SB(1, 0), cB + kstep, voffB); PG8_STAGE(PG8_SA(1, 0), cA + kstep, voffA); PG8_STAGE(PG8_SB(1, 1), cB + hstepB + kstep, voffB);
;     PG8_WAIT_V(6); PG8_BAR;
.LBB0_784:
	s_lshl_b64 s[6:7], s[78:79], 25
	v_readlane_b32 s18, v251, 21
	s_add_u32 s44, s18, s6
	v_readlane_b32 s6, v251, 22
	s_addc_u32 s45, s6, s7
	s_lshl_b32 s56, s78, 13
	v_readlane_b32 s24, v251, 39
	s_lshl_b64 s[6:7], s[56:57], 2
	v_readlane_b32 s26, v251, 41
	v_readlane_b32 s27, v251, 42
	s_add_u32 s6, s26, s6
	s_addc_u32 s7, s27, s7
	v_bfe_u32 v208, v10, 4, 2
	s_add_u32 s46, s6, 0x8000
	v_and_b32_e32 v1, 15, v10
	v_lshlrev_b32_e32 v17, 4, v208
	v_lshlrev_b32_e32 v10, 2, v10
	s_addc_u32 s47, s7, 0
	s_lshl_b32 s18, s4, 6
	v_lshl_or_b32 v17, v1, 6, v17
	s_lshl_b32 s4, s4, 13
	v_and_b32_e32 v10, 32, v10
	v_bitop3_b32 v18, v17, s4, v10 bitop3:0xde
	s_lshl_b32 s4, s5, 5
	s_and_b32 s19, s4, 0x60
	s_add_i32 m0, s11, 0x18000
	v_lshl_add_u64 v[8:9], v[8:9], 0, s[60:61]
	s_lshl_b32 s4, s19, 7
	s_nop 0
	global_load_lds_dwordx4 v[8:9], off
	v_lshl_add_u64 v[6:7], v[6:7], 0, s[60:61]
	s_add_i32 m0, s11, 0x1a000
	s_add_i32 s20, s11, 0x8000
	s_add_i32 s21, s11, 0xa000
	v_bitop3_b32 v209, v17, s4, v10 bitop3:0xde
	global_load_lds_dwordx4 v[6:7], off
	v_lshl_add_u64 v[2:3], v[2:3], 0, s[60:61]
	s_mov_b32 m0, s20
	s_add_u32 s4, s80, 0x80080
	global_load_lds_dwordx4 v[2:3], off
	v_lshl_add_u64 v[2:3], v[4:5], 0, s[60:61]
	s_mov_b32 m0, s21
	s_addc_u32 s5, s81, 0
	global_load_lds_dwordx4 v[2:3], off
	s_add_i32 m0, s11, 0x1c000
	v_lshl_add_u64 v[2:3], s[4:5], 0, v[170:171]
	global_load_lds_dwordx4 v[2:3], off
	v_lshl_add_u64 v[2:3], s[4:5], 0, v[174:175]
	s_add_i32 m0, s11, 0x1e000
	s_cmpk_lt_u32 s22, 0x100
	global_load_lds_dwordx4 v[2:3], off
	v_lshlrev_b32_e32 v2, 15, v11
	v_and_b32_e32 v2, 0xffff0000, v2
	v_lshl_add_u32 v2, v12, 12, v2
	v_and_b32_e32 v3, 1, v11
	v_lshl_or_b32 v2, v3, 6, v2
	v_lshl_add_u32 v176, v13, 1, v2
	v_lshlrev_b32_e32 v2, 15, v14
	v_and_b32_e32 v2, 0xffff0000, v2
	s_waitcnt vmcnt(6)
	v_lshl_add_u32 v2, v15, 12, v2
	v_and_b32_e32 v3, 1, v14
	v_lshl_or_b32 v2, v3, 6, v2
	s_cselect_b64 s[48:49], -1, 0
	v_mov_b32_e32 v177, v0
	v_lshl_add_u32 v178, v16, 1, v2
	v_mov_b32_e32 v179, v0
	s_mov_b32 s22, 0
	v_add_u32_e32 v210, 0, v18
	v_readlane_b32 s25, v251, 40
	s_barrier
	v_readfirstlane_b32 s98, v188
	s_cmp_lt_u32 s98, 0x100
	s_cbranch_scc1 .Lfill_skip6
	s_barrier
